# stack8 variant: P0 deferral on odd-XCD CUs (bit 0) instead of bit 3
# speedup vs baseline: 1.0079x; 1.0069x over previous
.LBB0_128:
	s_or_b64 exec, exec, s[0:1]
	s_bitcmp1_b32 s2, 0
	s_cbranch_scc0 .Lp1_skipdefer
	v_writelane_b32 v234, s0, 0
	v_writelane_b32 v234, s1, 1
	v_writelane_b32 v234, s2, 2
	v_writelane_b32 v234, s3, 3
	v_writelane_b32 v234, s4, 4
	v_writelane_b32 v234, s5, 5
	v_writelane_b32 v234, s6, 6
	v_writelane_b32 v234, s7, 7
	v_writelane_b32 v234, s8, 8
	v_writelane_b32 v234, s9, 9
	v_writelane_b32 v234, s10, 10
	v_writelane_b32 v234, s11, 11
	v_writelane_b32 v234, s12, 12
	v_writelane_b32 v234, s13, 13
	v_writelane_b32 v234, s14, 14
	v_writelane_b32 v234, s15, 15
	v_writelane_b32 v234, s16, 16
	v_writelane_b32 v234, s17, 17
	v_writelane_b32 v234, s18, 18
	v_writelane_b32 v234, s19, 19
	v_writelane_b32 v234, s20, 20
	v_writelane_b32 v234, s21, 21
	v_writelane_b32 v234, s22, 22
	v_writelane_b32 v234, s23, 23
	v_writelane_b32 v234, s24, 24
	v_writelane_b32 v234, s25, 25
	v_writelane_b32 v234, s26, 26
	v_writelane_b32 v234, s27, 27
	v_writelane_b32 v234, s28, 28
	v_writelane_b32 v234, s29, 29
	v_writelane_b32 v234, s30, 30
	v_writelane_b32 v234, s31, 31
	v_writelane_b32 v234, s32, 32
	v_writelane_b32 v234, s33, 33
	v_writelane_b32 v234, s34, 34
	v_writelane_b32 v234, s35, 35
	v_writelane_b32 v234, s36, 36
	v_writelane_b32 v234, s37, 37
	v_writelane_b32 v234, s38, 38
	v_writelane_b32 v234, s39, 39
	v_writelane_b32 v234, s40, 40
	v_writelane_b32 v234, s41, 41
	v_writelane_b32 v234, s42, 42
	v_writelane_b32 v234, s43, 43
	v_writelane_b32 v234, s44, 44
	v_writelane_b32 v234, s45, 45
	v_writelane_b32 v234, s46, 46
	v_writelane_b32 v234, s47, 47
	v_writelane_b32 v234, s48, 48
	v_writelane_b32 v234, s49, 49
	v_writelane_b32 v234, s50, 50
	v_writelane_b32 v234, s51, 51
	v_writelane_b32 v234, s52, 52
	v_writelane_b32 v234, s53, 53
	v_writelane_b32 v234, s54, 54
	v_writelane_b32 v234, s55, 55
	v_writelane_b32 v234, s56, 56
	v_writelane_b32 v234, s57, 57
	v_writelane_b32 v234, s58, 58
	v_writelane_b32 v234, s59, 59
	v_writelane_b32 v234, s60, 60
	v_writelane_b32 v234, s61, 61
	v_writelane_b32 v234, s62, 62
	v_writelane_b32 v234, s63, 63
	v_writelane_b32 v235, s64, 0
	v_writelane_b32 v235, s65, 1
	v_writelane_b32 v235, s66, 2
	v_writelane_b32 v235, s67, 3
	v_writelane_b32 v235, s68, 4
	v_writelane_b32 v235, s69, 5
	v_writelane_b32 v235, s70, 6
	v_writelane_b32 v235, s71, 7
	v_writelane_b32 v235, s72, 8
	v_writelane_b32 v235, s73, 9
	v_writelane_b32 v235, s74, 10
	v_writelane_b32 v235, s75, 11
	v_writelane_b32 v235, s76, 12
	v_writelane_b32 v235, s77, 13
	v_writelane_b32 v235, s78, 14
	v_writelane_b32 v235, s79, 15
	v_writelane_b32 v235, s80, 16
	v_writelane_b32 v235, s81, 17
	v_writelane_b32 v235, s82, 18
	v_writelane_b32 v235, s83, 19
	v_writelane_b32 v235, s84, 20
	v_writelane_b32 v235, s85, 21
	v_writelane_b32 v235, s86, 22
	v_writelane_b32 v235, s87, 23
	v_writelane_b32 v235, s88, 24
	v_writelane_b32 v235, s89, 25
	v_writelane_b32 v235, s90, 26
	v_writelane_b32 v235, s91, 27
	v_writelane_b32 v235, s92, 28
	v_writelane_b32 v235, s93, 29
	v_writelane_b32 v235, s94, 30
	v_writelane_b32 v235, s95, 31
	v_writelane_b32 v235, s96, 32
	v_writelane_b32 v235, s97, 33
	v_writelane_b32 v235, vcc_lo, 34
	v_writelane_b32 v235, vcc_hi, 35
	v_readlane_b32 s72, v233, 47
	v_readlane_b32 s73, v233, 48
	v_readlane_b32 s74, v233, 49
	v_readlane_b32 s75, v233, 50
	v_readlane_b32 s76, v233, 51
	v_readlane_b32 s77, v233, 52
	s_add_u32 s62, s92, 0x400000
	s_addc_u32 s63, s93, 0
	v_mov_b32_e32 v1, v210
	s_nop 0
	v_readfirstlane_b32 s0, v1
	v_and_b32_e32 v76, 63, v1
	s_nop 3
	s_ashr_i32 s8, s0, 6
	s_lshr_b32 s1, s2, 1
	s_lshl_b32 s1, s1, 0
	s_and_b32 s3, s2, 0
	s_or_b32 s1, s1, s3
	s_lshl_b32 s1, s1, 3
	s_add_i32 s26, s8, s1
	s_addk_i32 s26, 0x1000
	s_movk_i32 s96, 0x400
	s_movk_i32 s101, 0x247f
	s_mov_b32 s100, 1
	s_branch .Lp0_setup
